# sweep 1 far tiles: QK(keys 32-63) MFMAs interleaved into the statistics VALU of keys 0-31 (on top of sweep-2 interleave)
# baseline (speedup 1.0000x reference)
; #define KLOAD(t) do { const bf16* kp_ = Kb + (size_t)((t) * 64 + sr) * 1024 + sc; ks0 = *reinterpret_cast<const bf16x8*>(kp_); ks1 = *reinterpret_cast<const bf16x8*>(kp_ + 32 * 1024); } while (0)
; #define KWRITE() do { *reinterpret_cast<bf16x8*>(K_lds + kst0) = ks0; *reinterpret_cast<bf16x8*>(K_lds + kst1) = ks1; } while (0)
; template <bool DIFF> ...
;     ...
;   for (int t = t_lo; t < t_hi; ++t) {
;     __syncthreads();
;     KWRITE();
;     __syncthreads();
;     if (t + 1 < t_hi) KLOAD(t + 1);
;     const bool active = DIFF || (t >= rstart && t < rstart + 8);
;     if (active) {
;       f32x16 a0, b0, a1, b1;
;       qkt<DIFF>(a0, b0, K_lds, Q_lds, r32, r32, hi);
;       qkt<DIFF>(a1, b1, K_lds, Q_lds, r32 + 32, r32, hi);
.LBB0_276:
	v_add_u32_e32 v176, v97, v98
	s_waitcnt lgkmcnt(0)
	s_barrier
	s_waitcnt vmcnt(0)
	ds_write_b128 v174, v[64:67]
	ds_write_b128 v175, v[68:71]
	s_waitcnt lgkmcnt(0)
	s_barrier
	s_add_i32 s92, s2, s91
	s_cmpk_ge_i32 s92, 0x9f
	s_cbranch_scc1 .Lsw1f_hi
	s_cmpk_le_i32 s92, 0xff41
	s_cbranch_scc1 .Lsw1f_lo
	ds_read_b128 v[0:3], v176
	ds_read_b128 v[4:7], v172 offset:36864
	v_add_u32_e32 v177, v97, v93
	ds_read_b128 v[8:11], v177
	ds_read_b128 v[12:15], v176 offset:8192
	s_waitcnt lgkmcnt(2)
	v_mfma_f32_32x32x16_bf16 v[48:63], v[0:3], v[4:7], 0
	ds_read_b128 v[0:3], v171 offset:36864
	ds_read_b128 v[64:67], v177 offset:8192
	v_add_u32_e32 v178, v97, v90
	v_add_u32_e32 v179, v97, v94
	v_add_u32_e32 v180, v97, v91
	v_add_u32_e32 v181, v97, v95
	v_add_u32_e32 v182, v97, v92
	v_add_u32_e32 v183, v97, v96
	s_waitcnt lgkmcnt(1)
	v_mfma_f32_32x32x16_bf16 v[32:47], v[8:11], v[0:3], 0
	ds_read_b128 v[8:11], v178
	ds_read_b128 v[68:71], v170 offset:36864
	ds_read_b128 v[16:19], v179
	ds_read_b128 v[100:103], v178 offset:8192
	ds_read_b128 v[104:107], v169 offset:36864
	ds_read_b128 v[108:111], v179 offset:8192
	s_waitcnt lgkmcnt(1)
	v_mfma_f32_32x32x16_bf16 v[32:47], v[16:19], v[104:107], v[32:47]
	v_mfma_f32_32x32x16_bf16 v[48:63], v[8:11], v[68:71], v[48:63]
	ds_read_b128 v[8:11], v180
	ds_read_b128 v[112:115], v168 offset:36864
	ds_read_b128 v[16:19], v181
	ds_read_b128 v[116:119], v180 offset:8192
	ds_read_b128 v[120:123], v167 offset:36864
	ds_read_b128 v[124:127], v181 offset:8192
	s_waitcnt lgkmcnt(1)
	v_mfma_f32_32x32x16_bf16 v[32:47], v[16:19], v[120:123], v[32:47]
	v_mfma_f32_32x32x16_bf16 v[48:63], v[8:11], v[112:115], v[48:63]
	ds_read_b128 v[8:11], v182
	ds_read_b128 v[136:139], v166 offset:36864
	ds_read_b128 v[16:19], v183
	ds_read_b128 v[140:143], v182 offset:8192
	ds_read_b128 v[150:153], v149 offset:36864
	ds_read_b128 v[184:187], v183 offset:8192
	s_waitcnt lgkmcnt(1)
	v_mfma_f32_32x32x16_bf16 v[32:47], v[16:19], v[150:153], v[32:47]
	v_mfma_f32_32x32x16_bf16 v[16:31], v[12:15], v[4:7], 0
	v_mfma_f32_32x32x16_bf16 v[16:31], v[100:103], v[68:71], v[16:31]
	v_add_co_u32_e32 v68, vcc, s66, v84
	s_nop 1
	v_addc_co_u32_e32 v69, vcc, 0, v85, vcc
	global_load_dwordx4 v[68:71], v[68:69], off
	v_mfma_f32_32x32x16_bf16 v[48:63], v[8:11], v[136:139], v[48:63]
	v_mfma_f32_32x32x16_bf16 v[0:15], v[64:67], v[0:3], 0
	global_load_dwordx4 v[64:67], v[84:85], off
	v_mfma_f32_32x32x16_bf16 v[0:15], v[108:111], v[104:107], v[0:15]
	v_mfma_f32_32x32x16_bf16 v[16:31], v[116:119], v[112:115], v[16:31]
	v_mfma_f32_32x32x16_bf16 v[0:15], v[124:127], v[120:123], v[0:15]
	v_mfma_f32_32x32x16_bf16 v[16:31], v[140:143], v[136:139], v[16:31]
	s_waitcnt lgkmcnt(0)
	v_mfma_f32_32x32x16_bf16 v[0:15], v[184:187], v[150:153], v[0:15]
	s_add_i32 s92, s2, s91
	s_cmpk_ge_i32 s92, 0x9f
	s_cbranch_scc1 .Lb1a_hi
	s_cmpk_le_i32 s92, 0xff41
	s_cbranch_scc1 .Lb1a_lo
	v_add_u32_e32 v99, s2, v88
	v_add_u32_e32 v99, 0x80, v99
	v_med3_i32 v100, v99, 0, v163
	v_lshl_add_u32 v103, v100, 2, 0
	v_max_i32_e32 v100, -1, v99
	v_add_u32_e32 v100, 1, v100
	v_min_u32_e32 v100, 0x100, v100
	v_lshl_add_u32 v111, v100, 2, 0
	v_max_i32_e32 v100, -2, v99
	v_add_u32_e32 v100, 2, v100
	v_min_u32_e32 v100, 0x100, v100
	v_lshl_add_u32 v112, v100, 2, 0
	v_max_i32_e32 v100, -3, v99
	v_add_u32_e32 v100, 3, v100
	v_min_u32_e32 v100, 0x100, v100
	v_lshl_add_u32 v113, v100, 2, 0
	v_max_i32_e32 v100, -8, v99
	v_add_u32_e32 v100, 8, v100
	v_min_u32_e32 v100, 0x100, v100
	v_lshl_add_u32 v114, v100, 2, 0
	v_max_i32_e32 v100, -9, v99
	v_add_u32_e32 v100, 9, v100
	v_min_u32_e32 v100, 0x100, v100
	v_lshl_add_u32 v115, v100, 2, 0
	v_max_i32_e32 v100, -10, v99
	v_add_u32_e32 v100, 10, v100
	v_min_u32_e32 v100, 0x100, v100
	v_lshl_add_u32 v116, v100, 2, 0
	v_max_i32_e32 v100, -11, v99
	v_add_u32_e32 v100, 11, v100
	v_min_u32_e32 v100, 0x100, v100
	v_lshl_add_u32 v117, v100, 2, 0
	v_max_i32_e32 v100, -16, v99
	v_max_i32_e32 v101, 0xffffffef, v99
	v_max_i32_e32 v104, 0xffffffee, v99
	v_max_i32_e32 v105, 0xffffffed, v99
	v_max_i32_e32 v106, 0xffffffe8, v99
	v_max_i32_e32 v107, 0xffffffe7, v99
	v_max_i32_e32 v108, 0xffffffe6, v99
	v_add_u32_e32 v100, 16, v100
	v_add_u32_e32 v101, 17, v101
	v_add_u32_e32 v104, 18, v104
	v_add_u32_e32 v105, 19, v105
	v_add_u32_e32 v106, 24, v106
	v_add_u32_e32 v107, 25, v107
	v_add_u32_e32 v108, 26, v108
	v_max_i32_e32 v99, 0xffffffe5, v99
	v_min_u32_e32 v100, 0x100, v100
	v_min_u32_e32 v101, 0x100, v101
	v_min_u32_e32 v104, 0x100, v104
	v_min_u32_e32 v105, 0x100, v105
	v_min_u32_e32 v106, 0x100, v106
	v_min_u32_e32 v107, 0x100, v107
	v_min_u32_e32 v108, 0x100, v108
	v_add_u32_e32 v99, 27, v99
	v_lshl_add_u32 v100, v100, 2, 0
	v_lshl_add_u32 v101, v101, 2, 0
	v_lshl_add_u32 v104, v104, 2, 0
	v_lshl_add_u32 v105, v105, 2, 0
	v_lshl_add_u32 v106, v106, 2, 0
	v_lshl_add_u32 v107, v107, 2, 0
	v_lshl_add_u32 v108, v108, 2, 0
	v_min_u32_e32 v99, 0x100, v99
	v_lshl_add_u32 v99, v99, 2, 0
	ds_read_b32 v100, v100 offset:32768
	ds_read_b32 v101, v101 offset:32768
	ds_read_b32 v104, v104 offset:32768
	ds_read_b32 v105, v105 offset:32768
	ds_read_b32 v106, v106 offset:32768
	ds_read_b32 v107, v107 offset:32768
	ds_read_b32 v108, v108 offset:32768
	ds_read_b32 v109, v99 offset:32768
	ds_read_b32 v110, v103 offset:32768
	ds_read_b32 v111, v111 offset:32768
	ds_read_b32 v112, v112 offset:32768
	ds_read_b32 v113, v113 offset:32768
	ds_read_b32 v114, v114 offset:32768
	ds_read_b32 v115, v115 offset:32768
	ds_read_b32 v116, v116 offset:32768
	ds_read_b32 v117, v117 offset:32768
	s_waitcnt lgkmcnt(8)
	v_pk_add_f32 v[62:63], v[62:63], v[108:109]
	v_pk_add_f32 v[60:61], v[60:61], v[106:107]
	v_pk_add_f32 v[58:59], v[58:59], v[104:105]
	v_pk_add_f32 v[56:57], v[56:57], v[100:101]
	s_waitcnt lgkmcnt(0)
	v_pk_add_f32 v[54:55], v[54:55], v[116:117]
	v_pk_add_f32 v[52:53], v[52:53], v[114:115]
	v_pk_add_f32 v[50:51], v[50:51], v[112:113]
	v_pk_add_f32 v[48:49], v[48:49], v[110:111]
	v_pk_add_f32 v[46:47], v[46:47], v[108:109]
	v_pk_add_f32 v[44:45], v[44:45], v[106:107]
	v_pk_add_f32 v[42:43], v[42:43], v[104:105]
	v_pk_add_f32 v[40:41], v[40:41], v[100:101]
	v_pk_add_f32 v[38:39], v[38:39], v[116:117]
	v_pk_add_f32 v[36:37], v[36:37], v[114:115]
	v_pk_add_f32 v[34:35], v[34:35], v[112:113]
	v_pk_add_f32 v[32:33], v[32:33], v[110:111]
	v_mov_b32_e32 v99, 0
	s_branch .LBB0_284

; #define SBAR() __builtin_amdgcn_sched_barrier(0)
; __device__ __forceinline__ void stat_upd(const f32x16& p0, float& m, float& l, const float C, const float cb) {
;   float mx = p0[0];
; #pragma unroll
;   for (int r = 1; r < 16; ++r) mx = fmaxf(mx, p0[r]);
;   { auto rr = __builtin_amdgcn_permlane32_swap(__float_as_uint(mx), __float_as_uint(mx), false, false);
;     mx = fmaxf(__uint_as_float(rr[0]), __uint_as_float(rr[1])); }
;   mx += cb;
;   const float mn = fmaxf(m, mx), alpha = __builtin_amdgcn_exp2f((m - mn) * C), mnC = (cb - mn) * C; float s = 0.f;
; #pragma unroll
;   for (int r = 0; r < 16; ++r) s += __builtin_amdgcn_exp2f(fmaf(p0[r], C, mnC));
;   l = l * alpha + s; m = mn;
; }
; template <bool DIFF> ...
;     ...
;       qkt<DIFF>(a0, b0, K_lds, Q_lds, r32, r32, hi);
;       qkt<DIFF>(a1, b1, K_lds, Q_lds, r32 + 32, r32, hi);
;       SBAR();
;       float cb0, cb1;
;       BIAS_APPLY(t, 0, a0, b0, cb0);
;       stat_upd(a0, m1, l1, C, cb0);
;       if (DIFF) stat_upd(b0, m2, l2, C, cb0);
.Lsw1f_hi:
	v_mov_b32_e32 v235, v253
	v_mov_b32_e32 v241, v253
	s_branch .Lsw1f
.Lsw1f_lo:
	v_mov_b32_e32 v235, v252
	v_mov_b32_e32 v241, v252
.Lsw1f:
	ds_read_b128 v[0:3], v176
	ds_read_b128 v[4:7], v172 offset:36864
	v_add_u32_e32 v177, v97, v93
	ds_read_b128 v[8:11], v177
	ds_read_b128 v[12:15], v176 offset:8192
	s_waitcnt lgkmcnt(2)
	v_mfma_f32_32x32x16_bf16 v[48:63], v[0:3], v[4:7], 0
	ds_read_b128 v[0:3], v171 offset:36864
	ds_read_b128 v[64:67], v177 offset:8192
	v_add_u32_e32 v178, v97, v90
	v_add_u32_e32 v179, v97, v94
	v_add_u32_e32 v180, v97, v91
	v_add_u32_e32 v181, v97, v95
	v_add_u32_e32 v182, v97, v92
	v_add_u32_e32 v183, v97, v96
	s_waitcnt lgkmcnt(1)
	v_mfma_f32_32x32x16_bf16 v[32:47], v[8:11], v[0:3], 0
	ds_read_b128 v[8:11], v178
	ds_read_b128 v[68:71], v170 offset:36864
	ds_read_b128 v[16:19], v179
	ds_read_b128 v[100:103], v178 offset:8192
	ds_read_b128 v[104:107], v169 offset:36864
	ds_read_b128 v[108:111], v179 offset:8192
	s_waitcnt lgkmcnt(1)
	v_mfma_f32_32x32x16_bf16 v[32:47], v[16:19], v[104:107], v[32:47]
	v_mfma_f32_32x32x16_bf16 v[48:63], v[8:11], v[68:71], v[48:63]
	ds_read_b128 v[8:11], v180
	ds_read_b128 v[112:115], v168 offset:36864
	ds_read_b128 v[16:19], v181
	ds_read_b128 v[116:119], v180 offset:8192
	ds_read_b128 v[120:123], v167 offset:36864
	ds_read_b128 v[124:127], v181 offset:8192
	s_waitcnt lgkmcnt(1)
	v_mfma_f32_32x32x16_bf16 v[32:47], v[16:19], v[120:123], v[32:47]
	v_mfma_f32_32x32x16_bf16 v[48:63], v[8:11], v[112:115], v[48:63]
	ds_read_b128 v[8:11], v182
	ds_read_b128 v[136:139], v166 offset:36864
	ds_read_b128 v[16:19], v183
	ds_read_b128 v[140:143], v182 offset:8192
	ds_read_b128 v[150:153], v149 offset:36864
	ds_read_b128 v[184:187], v183 offset:8192
	s_waitcnt lgkmcnt(1)
	v_mfma_f32_32x32x16_bf16 v[32:47], v[16:19], v[150:153], v[32:47]
	v_mfma_f32_32x32x16_bf16 v[48:63], v[8:11], v[136:139], v[48:63]
	s_waitcnt lgkmcnt(0)
	v_mfma_f32_32x32x16_bf16 v[16:31], v[12:15], v[4:7], 0
	s_nop 10
	v_max_f32_e32 v236, v49, v49
	v_max_f32_e32 v237, v48, v48
	v_max_f32_e32 v236, v237, v236
	v_max3_f32 v236, v236, v50, v51
	v_max3_f32 v236, v236, v52, v53
	v_max3_f32 v236, v236, v54, v55
	v_max3_f32 v236, v236, v56, v57
	v_max3_f32 v236, v236, v58, v59
	v_max3_f32 v236, v236, v60, v61
	v_max3_f32 v239, v236, v62, v63
	v_max_f32_e32 v236, v33, v33
	v_mfma_f32_32x32x16_bf16 v[16:31], v[100:103], v[68:71], v[16:31]
	v_max_f32_e32 v237, v32, v32
	v_max_f32_e32 v236, v237, v236
	v_max3_f32 v236, v236, v34, v35
	v_max3_f32 v236, v236, v36, v37
	v_max3_f32 v236, v236, v38, v39
	v_max3_f32 v236, v236, v40, v41
	v_max3_f32 v236, v236, v42, v43
	v_max3_f32 v236, v236, v44, v45
	v_max3_f32 v236, v236, v46, v47
	v_mov_b32_e32 v240, v239
	v_mov_b32_e32 v237, v236
	s_nop 0
	v_permlane32_swap_b32_e32 v239, v240
	v_permlane32_swap_b32_e32 v236, v237
	v_max_f32_e32 v238, v239, v239
	v_mfma_f32_32x32x16_bf16 v[0:15], v[64:67], v[0:3], 0
	v_add_co_u32_e32 v68, vcc, s66, v84
	s_nop 1
	v_addc_co_u32_e32 v69, vcc, 0, v85, vcc
	global_load_dwordx4 v[68:71], v[68:69], off
	global_load_dwordx4 v[64:67], v[84:85], off
	v_max_f32_e32 v239, v240, v240
	v_max_f32_e32 v238, v238, v239
	s_waitcnt lgkmcnt(0)
	v_add_f32_e32 v238, v235, v238
	v_max_f32_e32 v239, v87, v87
	v_max_f32_e32 v240, v239, v238
	v_sub_f32_e32 v238, v235, v240
	v_mul_f32_e32 v238, 0x3e38aa3b, v238
	v_fmamk_f32 v48, v48, 0x3e38aa3b, v238
	v_exp_f32_e32 v48, v48
	v_fmamk_f32 v49, v49, 0x3e38aa3b, v238
	v_exp_f32_e32 v49, v49
	v_fmamk_f32 v50, v50, 0x3e38aa3b, v238
	v_mfma_f32_32x32x16_bf16 v[0:15], v[108:111], v[104:107], v[0:15]
	v_exp_f32_e32 v50, v50
	v_fmamk_f32 v51, v51, 0x3e38aa3b, v238
	v_exp_f32_e32 v51, v51
	v_add_f32_e32 v48, 0, v48
	v_add_f32_e32 v48, v49, v48
	v_fmamk_f32 v49, v52, 0x3e38aa3b, v238
	v_add_f32_e32 v48, v50, v48
	v_exp_f32_e32 v49, v49
	v_fmamk_f32 v50, v53, 0x3e38aa3b, v238
	v_add_f32_e32 v48, v51, v48
	v_exp_f32_e32 v50, v50
	v_mfma_f32_32x32x16_bf16 v[16:31], v[116:119], v[112:115], v[16:31]
	v_fmamk_f32 v51, v54, 0x3e38aa3b, v238
	v_exp_f32_e32 v51, v51
	v_fmamk_f32 v52, v55, 0x3e38aa3b, v238
	v_exp_f32_e32 v52, v52
	v_add_f32_e32 v48, v49, v48
	v_add_f32_e32 v48, v50, v48
	v_add_f32_e32 v48, v51, v48
	v_add_f32_e32 v49, v52, v48
	v_fmamk_f32 v48, v56, 0x3e38aa3b, v238
	v_exp_f32_e32 v51, v48
	v_fmamk_f32 v48, v57, 0x3e38aa3b, v238
	v_exp_f32_e32 v53, v48
	v_mfma_f32_32x32x16_bf16 v[0:15], v[124:127], v[120:123], v[0:15]
	v_fmamk_f32 v48, v58, 0x3e38aa3b, v238
	v_exp_f32_e32 v55, v48
	v_fmamk_f32 v48, v59, 0x3e38aa3b, v238
	v_exp_f32_e32 v57, v48
	v_fmamk_f32 v48, v60, 0x3e38aa3b, v238
	v_exp_f32_e32 v59, v48
	v_fmamk_f32 v48, v61, 0x3e38aa3b, v238
	v_exp_f32_e32 v61, v48
	v_fmamk_f32 v48, v62, 0x3e38aa3b, v238
	v_exp_f32_e32 v239, v48
	v_mfma_f32_32x32x16_bf16 v[16:31], v[140:143], v[136:139], v[16:31]
	v_sub_f32_e32 v48, v87, v240
	v_mul_f32_e32 v48, 0x3e38aa3b, v48
	v_exp_f32_e32 v243, v48
	v_max_f32_e32 v48, v236, v236
	v_max_f32_e32 v50, v237, v237
	v_max_f32_e32 v48, v48, v50
	v_add_f32_e32 v48, v235, v48
	v_max_f32_e32 v50, v81, v81
	v_max_f32_e32 v236, v50, v48
	v_sub_f32_e32 v48, v235, v236
	v_mul_f32_e32 v62, 0x3e38aa3b, v48
	v_fmamk_f32 v32, v32, 0x3e38aa3b, v62
	v_exp_f32_e32 v32, v32
	v_mfma_f32_32x32x16_bf16 v[0:15], v[184:187], v[150:153], v[0:15]
	v_fmamk_f32 v33, v33, 0x3e38aa3b, v62
	v_exp_f32_e32 v33, v33
	v_fmamk_f32 v34, v34, 0x3e38aa3b, v62
	v_exp_f32_e32 v34, v34
	v_fmamk_f32 v35, v35, 0x3e38aa3b, v62
	v_exp_f32_e32 v35, v35
	v_add_f32_e32 v32, 0, v32
	v_add_f32_e32 v32, v33, v32
	v_fmamk_f32 v33, v36, 0x3e38aa3b, v62
	v_add_f32_e32 v32, v34, v32
; __device__ __forceinline__ void stat_upd(const f32x16& p0, float& m, float& l, const float C, const float cb) {
;   float mx = p0[0];
; #pragma unroll
;   for (int r = 1; r < 16; ++r) mx = fmaxf(mx, p0[r]);
;   { auto rr = __builtin_amdgcn_permlane32_swap(__float_as_uint(mx), __float_as_uint(mx), false, false);
;     mx = fmaxf(__uint_as_float(rr[0]), __uint_as_float(rr[1])); }
;   mx += cb;
;   const float mn = fmaxf(m, mx), alpha = __builtin_amdgcn_exp2f((m - mn) * C), mnC = (cb - mn) * C; float s = 0.f;
; #pragma unroll
;   for (int r = 0; r < 16; ++r) s += __builtin_amdgcn_exp2f(fmaf(p0[r], C, mnC));
;   l = l * alpha + s; m = mn;
; }
; template <bool DIFF> ...
;     ...
;       BIAS_APPLY(t, 1, a1, b1, cb1);
;       stat_upd(a1, m1, l1, C, cb1);
;       if (DIFF) stat_upd(b1, m2, l2, C, cb1);
;     }
;   }
	v_exp_f32_e32 v33, v33
	v_fmamk_f32 v34, v37, 0x3e38aa3b, v62
	v_add_f32_e32 v32, v35, v32
	v_exp_f32_e32 v34, v34
	v_fmamk_f32 v35, v38, 0x3e38aa3b, v62
	v_exp_f32_e32 v35, v35
	v_add_f32_e32 v32, v33, v32
	v_add_f32_e32 v32, v34, v32
	v_max_f32_e32 v34, v17, v17
	v_add_f32_e32 v32, v35, v32
	v_max_f32_e32 v35, v16, v16
	v_fmamk_f32 v36, v39, 0x3e38aa3b, v62
	v_max_f32_e32 v34, v35, v34
	v_exp_f32_e32 v36, v36
	v_max3_f32 v34, v34, v18, v19
	v_max3_f32 v34, v34, v20, v21
	v_max3_f32 v34, v34, v22, v23
	v_max3_f32 v34, v34, v24, v25
	v_add_f32_e32 v48, v36, v32
	v_fmamk_f32 v32, v40, 0x3e38aa3b, v62
	v_max3_f32 v34, v34, v26, v27
	v_exp_f32_e32 v50, v32
	v_fmamk_f32 v32, v41, 0x3e38aa3b, v62
	v_max3_f32 v34, v34, v28, v29
	v_exp_f32_e32 v52, v32
	v_fmamk_f32 v32, v42, 0x3e38aa3b, v62
	v_max3_f32 v34, v34, v30, v31
	v_exp_f32_e32 v54, v32
	v_fmamk_f32 v32, v43, 0x3e38aa3b, v62
	v_mov_b32_e32 v35, v34
	v_exp_f32_e32 v56, v32
	v_fmamk_f32 v32, v44, 0x3e38aa3b, v62
	v_permlane32_swap_b32_e32 v34, v35
	v_exp_f32_e32 v58, v32
	v_fmamk_f32 v32, v45, 0x3e38aa3b, v62
	v_max_f32_e32 v35, v35, v35
	v_max_f32_e32 v34, v34, v34
	v_fmac_f32_e32 v238, 0x3e38aa3b, v63
	v_exp_f32_e32 v60, v32
	v_fmamk_f32 v32, v46, 0x3e38aa3b, v62
	v_max_f32_e32 v34, v34, v35
	v_exp_f32_e32 v63, v238
	v_exp_f32_e32 v238, v32
	v_sub_f32_e32 v32, v81, v236
	v_add_f32_e32 v34, v241, v34
	v_mul_f32_e32 v32, 0x3e38aa3b, v32
	v_max_f32_e32 v87, v240, v34
	v_exp_f32_e32 v242, v32
	v_pk_add_f32 v[32:33], v[50:51], v[48:49]
	v_sub_f32_e32 v34, v241, v87
	v_pk_add_f32 v[32:33], v[52:53], v[32:33]
	v_mul_f32_e32 v34, 0x3e38aa3b, v34
	v_fmac_f32_e32 v62, 0x3e38aa3b, v47
	v_pk_add_f32 v[32:33], v[54:55], v[32:33]
	v_fmamk_f32 v16, v16, 0x3e38aa3b, v34
	v_exp_f32_e32 v62, v62
	v_pk_add_f32 v[32:33], v[56:57], v[32:33]
	v_exp_f32_e32 v35, v16
	v_fmamk_f32 v16, v17, 0x3e38aa3b, v34
	v_pk_add_f32 v[32:33], v[58:59], v[32:33]
	v_exp_f32_e32 v36, v16
	v_fmamk_f32 v18, v18, 0x3e38aa3b, v34
	v_pk_add_f32 v[32:33], v[60:61], v[32:33]
	v_exp_f32_e32 v18, v18
	v_fmamk_f32 v19, v19, 0x3e38aa3b, v34
	v_pk_add_f32 v[32:33], v[238:239], v[32:33]
	v_exp_f32_e32 v19, v19
	v_fmamk_f32 v20, v20, 0x3e38aa3b, v34
	v_pk_add_f32 v[16:17], v[62:63], v[32:33]
	v_add_f32_e32 v32, 0, v35
	v_exp_f32_e32 v20, v20
	v_fmamk_f32 v21, v21, 0x3e38aa3b, v34
	v_add_f32_e32 v32, v36, v32
	v_exp_f32_e32 v21, v21
	v_add_f32_e32 v18, v18, v32
	v_add_f32_e32 v18, v19, v18
	v_add_f32_e32 v18, v20, v18
	v_add_f32_e32 v19, v21, v18
	v_fmamk_f32 v18, v22, 0x3e38aa3b, v34
	v_max_f32_e32 v20, v1, v1
	v_max_f32_e32 v22, v0, v0
	v_max_f32_e32 v20, v22, v20
	v_max3_f32 v20, v20, v2, v3
	v_max3_f32 v20, v20, v4, v5
	v_max3_f32 v20, v20, v6, v7
	v_max3_f32 v20, v20, v8, v9
	v_max3_f32 v20, v20, v10, v11
	v_max3_f32 v20, v20, v12, v13
	v_max3_f32 v20, v20, v14, v15
	v_exp_f32_e32 v21, v18
	v_fmamk_f32 v18, v23, 0x3e38aa3b, v34
	v_mov_b32_e32 v22, v20
	v_exp_f32_e32 v23, v18
	v_fmamk_f32 v18, v24, 0x3e38aa3b, v34
	v_permlane32_swap_b32_e32 v20, v22
	v_exp_f32_e32 v33, v18
	v_fmamk_f32 v18, v25, 0x3e38aa3b, v34
	v_max_f32_e32 v22, v22, v22
	v_max_f32_e32 v20, v20, v20
	v_exp_f32_e32 v25, v18
	v_fmamk_f32 v18, v26, 0x3e38aa3b, v34
	v_max_f32_e32 v20, v20, v22
	v_exp_f32_e32 v35, v18
	v_fmamk_f32 v18, v27, 0x3e38aa3b, v34
	v_add_f32_e32 v20, v241, v20
	v_exp_f32_e32 v27, v18
	v_fmamk_f32 v18, v28, 0x3e38aa3b, v34
	v_max_f32_e32 v81, v236, v20
	v_exp_f32_e32 v37, v18
	v_fmamk_f32 v18, v29, 0x3e38aa3b, v34
	v_sub_f32_e32 v20, v241, v81
	v_exp_f32_e32 v29, v18
	v_fmamk_f32 v18, v30, 0x3e38aa3b, v34
	v_mul_f32_e32 v30, 0x3e38aa3b, v20
	v_fmamk_f32 v0, v0, 0x3e38aa3b, v30
	v_exp_f32_e32 v0, v0
	v_fmamk_f32 v1, v1, 0x3e38aa3b, v30
	v_exp_f32_e32 v20, v1
	v_fmamk_f32 v2, v2, 0x3e38aa3b, v30
	v_exp_f32_e32 v2, v2
	v_fmamk_f32 v3, v3, 0x3e38aa3b, v30
	v_exp_f32_e32 v3, v3
	v_fmamk_f32 v4, v4, 0x3e38aa3b, v30
	v_add_f32_e32 v0, 0, v0
	v_exp_f32_e32 v4, v4
	v_fmamk_f32 v5, v5, 0x3e38aa3b, v30
	v_add_f32_e32 v0, v20, v0
	v_exp_f32_e32 v5, v5
	v_add_f32_e32 v0, v2, v0
	v_add_f32_e32 v0, v3, v0
	v_exp_f32_e32 v39, v18
	v_sub_f32_e32 v18, v240, v87
	v_add_f32_e32 v0, v4, v0
	v_mul_f32_e32 v1, 0x3e38aa3b, v18
	v_add_f32_e32 v18, v5, v0
	v_fmamk_f32 v0, v6, 0x3e38aa3b, v30
	v_exp_f32_e32 v20, v0
	v_fmamk_f32 v0, v7, 0x3e38aa3b, v30
	v_exp_f32_e32 v22, v0
	v_fmamk_f32 v0, v8, 0x3e38aa3b, v30
	v_exp_f32_e32 v32, v0
	v_fmamk_f32 v0, v9, 0x3e38aa3b, v30
	v_fmac_f32_e32 v34, 0x3e38aa3b, v31
	v_exp_f32_e32 v24, v0
	v_fmamk_f32 v0, v10, 0x3e38aa3b, v30
	v_exp_f32_e32 v31, v34
	v_exp_f32_e32 v34, v0
	v_fmamk_f32 v0, v11, 0x3e38aa3b, v30
	v_pk_add_f32 v[2:3], v[20:21], v[18:19]
	v_exp_f32_e32 v26, v0
	v_fmamk_f32 v0, v12, 0x3e38aa3b, v30
	v_pk_add_f32 v[2:3], v[22:23], v[2:3]
	v_exp_f32_e32 v36, v0
	v_fmamk_f32 v0, v13, 0x3e38aa3b, v30
	v_pk_add_f32 v[2:3], v[32:33], v[2:3]
	v_exp_f32_e32 v28, v0
	v_fmamk_f32 v0, v14, 0x3e38aa3b, v30
	v_pk_add_f32 v[2:3], v[24:25], v[2:3]
	v_exp_f32_e32 v38, v0
	v_fmac_f32_e32 v30, 0x3e38aa3b, v15
	v_sub_f32_e32 v0, v236, v81
	v_pk_add_f32 v[2:3], v[34:35], v[2:3]
	v_exp_f32_e32 v30, v30
	v_mul_f32_e32 v0, 0x3e38aa3b, v0
	v_pk_add_f32 v[2:3], v[26:27], v[2:3]
	v_exp_f32_e32 v1, v1
	v_exp_f32_e32 v0, v0
	v_pk_add_f32 v[2:3], v[36:37], v[2:3]
	v_pk_fma_f32 v[16:17], v[82:83], v[242:243], v[16:17]
	v_pk_add_f32 v[2:3], v[28:29], v[2:3]
	s_add_i32 s2, s2, 64
	v_pk_add_f32 v[2:3], v[38:39], v[2:3]
	s_cmp_eq_u32 s18, s2
	v_pk_add_f32 v[2:3], v[30:31], v[2:3]
	v_lshl_add_u64 v[84:85], v[84:85], 0, s[26:27]
	v_pk_fma_f32 v[82:83], v[16:17], v[0:1], v[2:3]
	s_cbranch_scc1 .LBB0_292
	s_branch .LBB0_276
